# 8 stagger classes by XCD index, ~0.85 us steps (s_sleep 32 per step)
# speedup vs baseline: 1.0015x; 1.0015x over previous
.LBB0_539:
	s_or_b64 exec, exec, s[0:1]
	v_mov_b32_e32 v0, v154
	v_readlane_b32 s6, v253, 0
	s_waitcnt lgkmcnt(0)
	s_barrier
	v_readlane_b32 s8, v253, 0
	s_and_b32 s8, s8, 7
	s_cmp_eq_u32 s8, 0
	s_cbranch_scc1 .Lxs_skip
.Lxs_loop:
	s_sleep 32
	s_sub_u32 s8, s8, 1
	s_cmp_lg_u32 s8, 0
	s_cbranch_scc1 .Lxs_loop
